# conv-branch items: workgroups ordered XCD-major so neighbouring row groups (shared halo rows) sit on one XCD
# speedup vs baseline: 1.0043x; 1.0005x over previous
.LBB0_327:
	s_or_b64 exec, exec, s[4:5]
	v_mov_b32_e32 v126, v164
	s_waitcnt lgkmcnt(0)
	s_barrier
	s_and_b32 s98, s2, 7
	s_lshl_b32 s98, s98, 5
	s_lshr_b32 s99, s2, 3
	s_add_i32 s98, s98, s99
	s_cmpk_lg_i32 s26, 0x100
	s_cselect_b32 s98, s2, s98
	s_add_u32 s14, s34, 0xc000000
	v_lshrrev_b32_e32 v154, 7, v126
	v_mul_u32_u24_e32 v154, s26, v154
	v_add_u32_e32 v154, s98, v154
	v_and_b32_e32 v155, 0x7f, v126
	v_lshl_add_u32 v94, v154, 7, v155
	s_mov_b32 s3, 0x48000
	s_addc_u32 s15, s35, 0
	s_mov_b32 s6, 12
	s_mov_b32 s4, 2
	v_cmp_gt_i32_e32 vcc, s3, v94
	v_lshlrev_b32_e32 v127, 3, v126
	s_and_saveexec_b64 s[8:9], vcc
	s_cbranch_execz .LBB0_340
	s_ashr_i32 s7, s6, 31
	s_lshl_b64 s[6:7], s[6:7], 3
	s_add_u32 s6, s0, s6
	s_addc_u32 s7, s1, s7
	s_ashr_i32 s5, s4, 31
	s_lshl_b64 s[4:5], s[4:5], 3
	s_add_u32 s4, s0, s4
	s_addc_u32 s5, s1, s5
	s_load_dwordx2 s[10:11], s[6:7], 0x0
	s_load_dwordx2 s[38:39], s[4:5], 0x0
	s_lshl_b32 s3, s26, 9
	v_lshlrev_b32_e32 v95, 3, v94
	s_lshl_b32 s19, s26, 12
	s_mov_b64 s[40:41], 0
	s_movk_i32 s25, 0x1fff
	s_movk_i32 s29, 0x2000
	v_mov_b32_e32 v96, 0x7fc
	v_mov_b32_e32 v49, 0
	s_movk_i32 s48, 0x4800
	s_movk_i32 s49, 0x1000
	s_mov_b64 s[42:43], 0x1000
	s_mov_b64 s[44:45], 0x2000
	s_mov_b32 s50, 0x17200000
	s_mov_b32 s51, 0x47fff
	v_mov_b32_e32 v97, 0x5808000
	v_mov_b32_e32 v98, 0x5800000
	s_branch .LBB0_330
